# P7 tail Wgu f32->bf16 transposing conversion: job order remapped so the 8 waves of a workgroup take 8 adjacent k-tiles of one n-tile (1 KB contiguous output runs)
# baseline (speedup 1.0000x reference)
; __device__ __forceinline__ void tr_convert(Frame& F, ArgsP a, int lo, int hi, int w0, int nw) {
;     ...
;         if (r < TJGU) { const int kb = r / 344, nb = r % 344; const int n0 = nb * 64, pn = n0 >> 8, rr = n0 & 255; const bool up = rr >= 128;
;             t.W = (const float*)a->in[up ? I_WFU : I_WFG]; t.ldw = DFF; t.K = DM; t.WT = (bf16_t*)(a->ws + WS_WGU); t.gain = (const float*)a->in[I_GFFN]; t.n0 = n0; t.k0 = kb * 64; t.scol4 = pn * 128 + (rr & 127) + c4; return t; } r -= TJGU;
;     ...
;     f32x4 v[16]; int it = lo + w0;
;     if (it < hi) { TrItem cur = mk(it); tr_load(cur, v, F.lane);
.LBB0_1662:
	s_cmpk_gt_i32 s58, 0x55ff
	s_cbranch_scc1 .LBB0_1746
	s_add_i32 s33, s58, 0x6400
	s_cmpk_gt_i32 s58, 0xdaff
	v_and_b32_e32 v1, 60, v1
	s_cbranch_scc0 .LBB0_1669
	s_cmpk_gt_u32 s33, 0x42ff
	s_cbranch_scc0 .LBB0_1670
	s_cmpk_gt_u32 s33, 0x43ff
	s_cbranch_scc0 .LBB0_1671
	s_cmpk_gt_u32 s33, 0x53ff
	s_cbranch_scc0 .LBB0_1672
	s_cmp_lt_u32 s58, 0xffff9c00
	s_cbranch_scc0 .LBB0_1673
	s_add_i32 s0, s33, 0x9c00
	s_and_b32 s1, s0, 0xffff
	s_lshr_b32 s99, s1, 3
	s_and_b32 s1, s1, 7
	s_mul_i32 s18, s99, 0xbe83
	s_lshr_b32 s18, s18, 24
	s_mul_i32 s0, s18, 0x158
	s_sub_i32 s0, s99, s0
	s_lshl_b32 s18, s18, 3
	s_or_b32 s18, s18, s1
	s_and_b32 s19, s0, 0xffff
	s_lshl_b32 s20, s19, 6
	s_bitcmp0_b32 s0, 1
	s_movk_i32 s0, 0x98
	s_cselect_b32 s0, s0, 0xa0
	s_add_u32 s16, s6, s0
	s_addc_u32 s17, s7, 0
	s_load_dwordx2 s[2:3], s[16:17], 0x0
	s_load_dwordx2 s[14:15], s[6:7], 0x90
	s_add_u32 s0, s8, 0x1e200000
	s_addc_u32 s1, s9, 0
	s_lshl_b32 s16, s19, 5
	s_and_b32 s16, s16, 0x3f80
	s_and_b32 s17, s20, 64
	s_lshl_b32 s18, s18, 6
	s_or_b32 s16, s16, s17
	v_or_b32_e32 v67, s16, v1
	s_mov_b64 s[16:17], 0
	v_mov_b32_e32 v200, s20
	v_mov_b32_e32 v66, s18
	s_branch .LBB0_1674

; __device__ __forceinline__ void tr_convert(Frame& F, ArgsP a, int lo, int hi, int w0, int nw) {
;     ...
;         if (r < TJGU) { const int kb = r / 344, nb = r % 344; const int n0 = nb * 64, pn = n0 >> 8, rr = n0 & 255; const bool up = rr >= 128;
;             t.W = (const float*)a->in[up ? I_WFU : I_WFG]; t.ldw = DFF; t.K = DM; t.WT = (bf16_t*)(a->ws + WS_WGU); t.gain = (const float*)a->in[I_GFFN]; t.n0 = n0; t.k0 = kb * 64; t.scol4 = pn * 128 + (rr & 127) + c4; return t; } r -= TJGU;
;     ...
;         for (;;) { const int nx = it + nw; f32x4 w[16];
; #pragma unroll
;             for (int q = 0; q < 16; ++q) w[q] = v[q];
;             TrItem nxt = cur; const bool more = nx < hi; if (more) { nxt = mk(nx); tr_load(nxt, v, F.lane); }
.LBB0_1706:
	s_add_i32 s42, s33, s54
	s_cmp_lt_i32 s42, 0xba00
	s_cselect_b64 s[20:21], -1, 0
	s_cmp_gt_i32 s42, 0xb9ff
	s_cselect_b64 s[18:19], -1, 0
	s_and_b64 vcc, exec, s[18:19]
	v_mov_b32_e32 v137, v133
	v_mov_b32_e32 v136, v132
	v_mov_b32_e32 v139, v135
	v_mov_b32_e32 v138, v134
	v_mov_b32_e32 v141, v129
	v_mov_b32_e32 v140, v128
	v_mov_b32_e32 v143, v131
	v_mov_b32_e32 v142, v130
	v_mov_b32_e32 v145, v125
	v_mov_b32_e32 v144, v124
	v_mov_b32_e32 v147, v127
	v_mov_b32_e32 v146, v126
	v_mov_b32_e32 v149, v121
	v_mov_b32_e32 v148, v120
	v_mov_b32_e32 v151, v123
	v_mov_b32_e32 v150, v122
	v_mov_b32_e32 v153, v117
	v_mov_b32_e32 v152, v116
	v_mov_b32_e32 v155, v119
	v_mov_b32_e32 v154, v118
	v_mov_b32_e32 v157, v113
	v_mov_b32_e32 v156, v112
	v_mov_b32_e32 v159, v115
	v_mov_b32_e32 v158, v114
	v_mov_b32_e32 v161, v109
	v_mov_b32_e32 v160, v108
	v_mov_b32_e32 v163, v111
	v_mov_b32_e32 v162, v110
	v_mov_b32_e32 v165, v105
	v_mov_b32_e32 v164, v104
	v_mov_b32_e32 v167, v107
	v_mov_b32_e32 v166, v106
	v_mov_b32_e32 v169, v101
	v_mov_b32_e32 v168, v100
	v_mov_b32_e32 v171, v103
	v_mov_b32_e32 v170, v102
	v_mov_b32_e32 v173, v97
	v_mov_b32_e32 v172, v96
	v_mov_b32_e32 v175, v99
	v_mov_b32_e32 v174, v98
	v_mov_b32_e32 v177, v93
	v_mov_b32_e32 v176, v92
	v_mov_b32_e32 v179, v95
	v_mov_b32_e32 v178, v94
	v_mov_b32_e32 v181, v89
	v_mov_b32_e32 v180, v88
	v_mov_b32_e32 v183, v91
	v_mov_b32_e32 v182, v90
	v_mov_b32_e32 v185, v85
	v_mov_b32_e32 v184, v84
	v_mov_b32_e32 v187, v87
	v_mov_b32_e32 v186, v86
	v_mov_b32_e32 v189, v81
	v_mov_b32_e32 v188, v80
	v_mov_b32_e32 v191, v83
	v_mov_b32_e32 v190, v82
	v_mov_b32_e32 v193, v77
	v_mov_b32_e32 v192, v76
	v_mov_b32_e32 v195, v79
	v_mov_b32_e32 v194, v78
	v_mov_b32_e32 v197, v73
	v_mov_b32_e32 v196, v72
	v_mov_b32_e32 v199, v75
	v_mov_b32_e32 v198, v74
	s_mov_b64 s[22:23], s[0:1]
	v_mov_b32_e32 v215, v201
	v_mov_b32_e32 v213, v200
	v_mov_b32_e32 v214, v66
	s_cbranch_vccnz .LBB0_1744
	s_cmpk_gt_i32 s42, 0x3eff
	s_mov_b64 s[30:31], -1
	s_cbranch_scc0 .LBB0_1725
	s_cmpk_gt_u32 s42, 0x42ff
	s_cbranch_scc0 .LBB0_1722
	s_cmpk_gt_u32 s42, 0x43ff
	s_cbranch_scc0 .LBB0_1719
	s_cmpk_gt_u32 s42, 0x53ff
	s_cbranch_scc0 .LBB0_1716
	s_cmpk_gt_u32 s42, 0x63ff
	s_mov_b64 s[22:23], -1
	s_cbranch_scc0 .LBB0_1713
	s_add_i32 s22, s42, 0x9c00
	s_and_b32 s23, s22, 0xffff
	s_lshr_b32 s99, s23, 3
	s_and_b32 s23, s23, 7
	s_mul_i32 s28, s99, 0xbe83
	s_lshr_b32 s28, s28, 24
	s_mul_i32 s22, s28, 0x158
	s_sub_i32 s22, s99, s22
	s_lshl_b32 s28, s28, 3
	s_or_b32 s28, s28, s23
	s_and_b32 s29, s22, 0xffff
	s_lshl_b32 s30, s29, 6
	s_bitcmp0_b32 s22, 1
	s_cselect_b32 s22, s34, 0xa0
	s_add_u32 s22, s6, s22
	s_addc_u32 s23, s7, 0
	s_load_dwordx2 s[24:25], s[22:23], 0x0
	s_load_dwordx2 s[26:27], s[6:7], 0x90
	s_lshl_b32 s22, s29, 5
	s_and_b32 s22, s22, 0x3f80
	s_and_b32 s23, s30, 64
	s_lshl_b32 s28, s28, 6
	s_or_b32 s22, s22, s23
	v_or_b32_e32 v67, s22, v1
	s_mov_b64 s[22:23], 0
	v_mov_b32_e32 v213, s30
	v_mov_b32_e32 v214, s28
